# out-proj and down GEMM epilogue stores write-through (sc1) so the grid barrier's L2 write-back has little dirty data
# baseline (speedup 1.0000x reference)
.LBB0_387:
	v_lshlrev_b64 v[148:149], 11, v[144:145]
	v_lshl_add_u64 v[148:149], s[54:55], 0, v[148:149]
	v_lshlrev_b64 v[160:161], 1, v[146:147]
	v_lshl_add_u64 v[148:149], v[148:149], 0, v[160:161]
	v_cvt_pk_bf16_f32 v156, v124, v125
	v_cvt_pk_bf16_f32 v157, v126, v127
	v_cvt_pk_bf16_f32 v158, v120, v121
	v_cvt_pk_bf16_f32 v159, v122, v123
	global_store_dwordx4 v[148:149], v[156:159], off sc1
	s_mov_b32 s1, 0x40000
	s_mov_b64 s[16:17], 0x40000
	v_cvt_pk_bf16_f32 v156, v108, v109
	v_cvt_pk_bf16_f32 v157, v110, v111
	v_cvt_pk_bf16_f32 v158, v104, v105
	v_cvt_pk_bf16_f32 v159, v106, v107
	global_store_dwordx4 v[148:149], v[156:159], off offset:256 sc1
	s_nop 1
	v_or_b32_e32 v156, 16, v144
	v_ashrrev_i32_e32 v157, 31, v156
	v_lshlrev_b64 v[156:157], 11, v[156:157]
	v_lshl_add_u64 v[156:157], s[54:55], 0, v[156:157]
	v_lshl_add_u64 v[162:163], v[156:157], 0, v[160:161]
	v_cvt_pk_bf16_f32 v156, v116, v117
	v_cvt_pk_bf16_f32 v157, v118, v119
	v_cvt_pk_bf16_f32 v158, v112, v113
	v_cvt_pk_bf16_f32 v159, v114, v115
	global_store_dwordx4 v[162:163], v[156:159], off sc1
	s_nop 1
	v_cvt_pk_bf16_f32 v156, v92, v93
	v_cvt_pk_bf16_f32 v157, v94, v95
	v_cvt_pk_bf16_f32 v158, v88, v89
	v_cvt_pk_bf16_f32 v159, v90, v91
	global_store_dwordx4 v[162:163], v[156:159], off offset:256 sc1
	s_nop 1
	v_or_b32_e32 v156, 32, v144
	v_ashrrev_i32_e32 v157, 31, v156
	v_lshlrev_b64 v[156:157], 11, v[156:157]
	v_lshl_add_u64 v[156:157], s[54:55], 0, v[156:157]
	v_lshl_add_u64 v[162:163], v[156:157], 0, v[160:161]
	v_cvt_pk_bf16_f32 v156, v100, v101
	v_cvt_pk_bf16_f32 v157, v102, v103
	v_cvt_pk_bf16_f32 v158, v96, v97
	v_cvt_pk_bf16_f32 v159, v98, v99
	global_store_dwordx4 v[162:163], v[156:159], off sc1
	s_nop 1
	v_cvt_pk_bf16_f32 v156, v76, v77
	v_cvt_pk_bf16_f32 v157, v78, v79
	v_cvt_pk_bf16_f32 v158, v72, v73
	v_cvt_pk_bf16_f32 v159, v74, v75
	global_store_dwordx4 v[162:163], v[156:159], off offset:256 sc1
	v_add_co_u32_e32 v162, vcc, s1, v148
	s_nop 0
	v_or_b32_e32 v156, 48, v144
	v_ashrrev_i32_e32 v157, 31, v156
	v_lshlrev_b64 v[156:157], 11, v[156:157]
	v_lshl_add_u64 v[156:157], s[54:55], 0, v[156:157]
	v_lshl_add_u64 v[160:161], v[156:157], 0, v[160:161]
	v_cvt_pk_bf16_f32 v156, v84, v85
	v_cvt_pk_bf16_f32 v157, v86, v87
	v_cvt_pk_bf16_f32 v158, v80, v81
	v_cvt_pk_bf16_f32 v159, v82, v83
	global_store_dwordx4 v[160:161], v[156:159], off sc1
	v_addc_co_u32_e32 v163, vcc, 0, v149, vcc
	s_nop 0
	v_cvt_pk_bf16_f32 v156, v68, v69
	v_cvt_pk_bf16_f32 v157, v70, v71
	v_cvt_pk_bf16_f32 v158, v64, v65
	v_cvt_pk_bf16_f32 v159, v66, v67
	global_store_dwordx4 v[160:161], v[156:159], off offset:256 sc1
	s_mov_b32 s1, 0x48000
	v_lshl_add_u64 v[160:161], v[148:149], 0, s[16:17]
	v_cvt_pk_bf16_f32 v156, v60, v61
	v_cvt_pk_bf16_f32 v157, v62, v63
	v_cvt_pk_bf16_f32 v158, v56, v57
	v_cvt_pk_bf16_f32 v159, v58, v59
	global_store_dwordx4 v[162:163], v[156:159], off sc1
	v_add_co_u32_e32 v162, vcc, s1, v148
	s_nop 0
	v_cvt_pk_bf16_f32 v156, v44, v45
	v_cvt_pk_bf16_f32 v157, v46, v47
	v_cvt_pk_bf16_f32 v158, v40, v41
	v_cvt_pk_bf16_f32 v159, v42, v43
	global_store_dwordx4 v[160:161], v[156:159], off offset:256 sc1
	s_mov_b64 s[16:17], 0x48000
	v_addc_co_u32_e32 v163, vcc, 0, v149, vcc
	v_cvt_pk_bf16_f32 v156, v52, v53
	v_cvt_pk_bf16_f32 v157, v54, v55
	v_cvt_pk_bf16_f32 v158, v48, v49
	v_cvt_pk_bf16_f32 v159, v50, v51
	s_mov_b32 s1, 0x50000
	v_lshl_add_u64 v[160:161], v[148:149], 0, s[16:17]
	global_store_dwordx4 v[162:163], v[156:159], off sc1
	s_mov_b64 s[16:17], 0x50000
	v_add_co_u32_e32 v162, vcc, s1, v148
	v_cvt_pk_bf16_f32 v156, v28, v29
	v_cvt_pk_bf16_f32 v157, v30, v31
	v_cvt_pk_bf16_f32 v158, v24, v25
	v_cvt_pk_bf16_f32 v159, v26, v27
	global_store_dwordx4 v[160:161], v[156:159], off offset:256 sc1
	v_lshl_add_u64 v[160:161], v[148:149], 0, s[16:17]
	v_addc_co_u32_e32 v163, vcc, 0, v149, vcc
	v_cvt_pk_bf16_f32 v156, v36, v37
	v_cvt_pk_bf16_f32 v157, v38, v39
	v_cvt_pk_bf16_f32 v158, v32, v33
	v_cvt_pk_bf16_f32 v159, v34, v35
	s_mov_b64 s[16:17], 0x58000
	s_mov_b32 s1, 0x58000
	global_store_dwordx4 v[162:163], v[156:159], off sc1
	s_nop 1
	v_cvt_pk_bf16_f32 v156, v12, v13
	v_cvt_pk_bf16_f32 v157, v14, v15
	v_cvt_pk_bf16_f32 v158, v8, v9
	v_cvt_pk_bf16_f32 v159, v10, v11
	global_store_dwordx4 v[160:161], v[156:159], off offset:256 sc1
	v_lshl_add_u64 v[160:161], v[148:149], 0, s[16:17]
	v_add_co_u32_e32 v148, vcc, s1, v148
	v_cvt_pk_bf16_f32 v156, v20, v21
	v_cvt_pk_bf16_f32 v157, v22, v23
	v_cvt_pk_bf16_f32 v158, v16, v17
	v_cvt_pk_bf16_f32 v159, v18, v19
	s_nop 1
	v_addc_co_u32_e32 v149, vcc, 0, v149, vcc
	global_store_dwordx4 v[148:149], v[156:159], off sc1
	s_nop 1
	v_cvt_pk_bf16_f32 v156, v4, v5
	v_cvt_pk_bf16_f32 v157, v6, v7
	v_cvt_pk_bf16_f32 v158, v0, v1
	v_cvt_pk_bf16_f32 v159, v2, v3
	global_store_dwordx4 v[160:161], v[156:159], off offset:256 sc1
	s_cbranch_execnz .LBB0_386
.LBB0_388:
	s_ashr_i32 s1, s0, 31
	s_lshl_b64 s[0:1], s[0:1], 21
	s_add_u32 s0, s90, s0
	s_addc_u32 s1, s91, s1
	v_lshl_add_u64 v[146:147], v[146:147], 2, s[0:1]
	v_lshlrev_b64 v[144:145], 12, v[144:145]
	s_brev_b32 s0, 63
	v_lshl_add_u64 v[144:145], v[146:147], 0, v[144:145]
	s_mov_b32 s1, -1
	v_lshl_add_u64 v[146:147], v[144:145], 0, s[0:1]
	s_brev_b32 s0, 63
	v_add_co_u32_e32 v148, vcc, s0, v144
	s_mov_b32 s0, 0xfc010000
	s_nop 0
	v_addc_co_u32_e32 v149, vcc, -1, v145, vcc
	s_mov_b32 s1, -1
	global_store_dwordx4 v[148:149], v[124:127], off sc1
	global_store_dwordx4 v[146:147], v[120:123], off offset:16 sc1
	global_store_dwordx4 v[146:147], v[108:111], off offset:512 sc1
	global_store_dwordx4 v[146:147], v[104:107], off offset:528 sc1
	s_nop 1
	v_lshl_add_u64 v[104:105], v[144:145], 0, s[0:1]
	s_mov_b32 s0, 0xfc010000
	v_add_co_u32_e32 v106, vcc, s0, v144
	s_mov_b32 s0, 0xfc020000
	s_nop 0
	v_addc_co_u32_e32 v107, vcc, -1, v145, vcc
	s_mov_b32 s1, -1
	global_store_dwordx4 v[106:107], v[116:119], off sc1
	global_store_dwordx4 v[104:105], v[112:115], off offset:16 sc1
	global_store_dwordx4 v[104:105], v[92:95], off offset:512 sc1
	global_store_dwordx4 v[104:105], v[88:91], off offset:528 sc1
	s_nop 1
	v_lshl_add_u64 v[88:89], v[144:145], 0, s[0:1]
	s_mov_b32 s0, 0xfc020000
	v_add_co_u32_e32 v90, vcc, s0, v144
	s_mov_b32 s0, 0xfc030000
	s_nop 0
	v_addc_co_u32_e32 v91, vcc, -1, v145, vcc
	s_mov_b32 s1, -1
	global_store_dwordx4 v[90:91], v[100:103], off sc1
	global_store_dwordx4 v[88:89], v[96:99], off offset:16 sc1
	global_store_dwordx4 v[88:89], v[76:79], off offset:512 sc1
	global_store_dwordx4 v[88:89], v[72:75], off offset:528 sc1
	s_nop 1
	v_lshl_add_u64 v[72:73], v[144:145], 0, s[0:1]
	s_mov_b32 s0, 0xfc030000
	v_add_co_u32_e32 v74, vcc, s0, v144
	s_mov_b32 s0, 0xfc080000
	s_nop 0
	v_addc_co_u32_e32 v75, vcc, -1, v145, vcc
	s_mov_b32 s1, -1
	global_store_dwordx4 v[74:75], v[84:87], off sc1
	global_store_dwordx4 v[72:73], v[80:83], off offset:16 sc1
	global_store_dwordx4 v[72:73], v[68:71], off offset:512 sc1
	global_store_dwordx4 v[72:73], v[64:67], off offset:528 sc1
	s_nop 1
	v_lshl_add_u64 v[64:65], v[144:145], 0, s[0:1]
	s_mov_b32 s0, 0xfc080000
	v_add_co_u32_e32 v66, vcc, s0, v144
	s_mov_b32 s0, 0xfc090000
	s_nop 0
	v_addc_co_u32_e32 v67, vcc, -1, v145, vcc
	s_mov_b32 s1, -1
	global_store_dwordx4 v[66:67], v[60:63], off sc1
	global_store_dwordx4 v[64:65], v[56:59], off offset:16 sc1
	global_store_dwordx4 v[64:65], v[44:47], off offset:512 sc1
	global_store_dwordx4 v[64:65], v[40:43], off offset:528 sc1
	s_nop 1
	v_lshl_add_u64 v[40:41], v[144:145], 0, s[0:1]
	s_mov_b32 s0, 0xfc090000
	v_add_co_u32_e32 v42, vcc, s0, v144
	s_mov_b32 s0, 0xfc0a0000
	s_nop 0
	v_addc_co_u32_e32 v43, vcc, -1, v145, vcc
	global_store_dwordx4 v[42:43], v[52:55], off sc1
	global_store_dwordx4 v[40:41], v[48:51], off offset:16 sc1
	global_store_dwordx4 v[40:41], v[28:31], off offset:512 sc1
	global_store_dwordx4 v[40:41], v[24:27], off offset:528 sc1
	s_mov_b32 s1, -1
	s_nop 0
	v_add_co_u32_e32 v26, vcc, 0xfc0a0000, v144
	v_lshl_add_u64 v[24:25], v[144:145], 0, s[0:1]
	s_nop 0
	v_addc_co_u32_e32 v27, vcc, -1, v145, vcc
	global_store_dwordx4 v[26:27], v[36:39], off sc1
	global_store_dwordx4 v[24:25], v[32:35], off offset:16 sc1
	global_store_dwordx4 v[24:25], v[12:15], off offset:512 sc1
	global_store_dwordx4 v[24:25], v[8:11], off offset:528 sc1
	s_mov_b32 s0, 0xfc0b0000
	s_mov_b32 s1, -1
	v_add_co_u32_e32 v10, vcc, 0xfc0b0000, v144
	v_lshl_add_u64 v[8:9], v[144:145], 0, s[0:1]
	s_nop 0
	v_addc_co_u32_e32 v11, vcc, -1, v145, vcc
	global_store_dwordx4 v[10:11], v[20:23], off sc1
	global_store_dwordx4 v[8:9], v[16:19], off offset:16 sc1
	global_store_dwordx4 v[8:9], v[4:7], off offset:512 sc1
	global_store_dwordx4 v[8:9], v[0:3], off offset:528 sc1
	s_and_b64 vcc, exec, s[6:7]
	s_mov_b64 s[0:1], -1
	s_cbranch_vccnz .LBB0_370

.LBB0_662:
	v_lshlrev_b64 v[148:149], 11, v[144:145]
	v_lshl_add_u64 v[148:149], s[54:55], 0, v[148:149]
	v_lshlrev_b64 v[160:161], 1, v[146:147]
	v_lshl_add_u64 v[148:149], v[148:149], 0, v[160:161]
	v_cvt_pk_bf16_f32 v156, v124, v125
	v_cvt_pk_bf16_f32 v157, v126, v127
	v_cvt_pk_bf16_f32 v158, v120, v121
	v_cvt_pk_bf16_f32 v159, v122, v123
	global_store_dwordx4 v[148:149], v[156:159], off sc1
	s_mov_b32 s1, 0x40000
	s_mov_b64 s[18:19], 0x40000
	v_cvt_pk_bf16_f32 v156, v108, v109
	v_cvt_pk_bf16_f32 v157, v110, v111
	v_cvt_pk_bf16_f32 v158, v104, v105
	v_cvt_pk_bf16_f32 v159, v106, v107
	global_store_dwordx4 v[148:149], v[156:159], off offset:256 sc1
	s_nop 1
	v_or_b32_e32 v156, 16, v144
	v_ashrrev_i32_e32 v157, 31, v156
	v_lshlrev_b64 v[156:157], 11, v[156:157]
	v_lshl_add_u64 v[156:157], s[54:55], 0, v[156:157]
	v_lshl_add_u64 v[162:163], v[156:157], 0, v[160:161]
	v_cvt_pk_bf16_f32 v156, v116, v117
	v_cvt_pk_bf16_f32 v157, v118, v119
	v_cvt_pk_bf16_f32 v158, v112, v113
	v_cvt_pk_bf16_f32 v159, v114, v115
	global_store_dwordx4 v[162:163], v[156:159], off sc1
	s_nop 1
	v_cvt_pk_bf16_f32 v156, v92, v93
	v_cvt_pk_bf16_f32 v157, v94, v95
	v_cvt_pk_bf16_f32 v158, v88, v89
	v_cvt_pk_bf16_f32 v159, v90, v91
	global_store_dwordx4 v[162:163], v[156:159], off offset:256 sc1
	s_nop 1
	v_or_b32_e32 v156, 32, v144
	v_ashrrev_i32_e32 v157, 31, v156
	v_lshlrev_b64 v[156:157], 11, v[156:157]
	v_lshl_add_u64 v[156:157], s[54:55], 0, v[156:157]
	v_lshl_add_u64 v[162:163], v[156:157], 0, v[160:161]
	v_cvt_pk_bf16_f32 v156, v100, v101
	v_cvt_pk_bf16_f32 v157, v102, v103
	v_cvt_pk_bf16_f32 v158, v96, v97
	v_cvt_pk_bf16_f32 v159, v98, v99
	global_store_dwordx4 v[162:163], v[156:159], off sc1
	s_nop 1
	v_cvt_pk_bf16_f32 v156, v76, v77
	v_cvt_pk_bf16_f32 v157, v78, v79
	v_cvt_pk_bf16_f32 v158, v72, v73
	v_cvt_pk_bf16_f32 v159, v74, v75
	global_store_dwordx4 v[162:163], v[156:159], off offset:256 sc1
	v_add_co_u32_e32 v162, vcc, s1, v148
	s_nop 0
	v_or_b32_e32 v156, 48, v144
	v_ashrrev_i32_e32 v157, 31, v156
	v_lshlrev_b64 v[156:157], 11, v[156:157]
	v_lshl_add_u64 v[156:157], s[54:55], 0, v[156:157]
	v_lshl_add_u64 v[160:161], v[156:157], 0, v[160:161]
	v_cvt_pk_bf16_f32 v156, v84, v85
	v_cvt_pk_bf16_f32 v157, v86, v87
	v_cvt_pk_bf16_f32 v158, v80, v81
	v_cvt_pk_bf16_f32 v159, v82, v83
	global_store_dwordx4 v[160:161], v[156:159], off sc1
	v_addc_co_u32_e32 v163, vcc, 0, v149, vcc
	s_nop 0
	v_cvt_pk_bf16_f32 v156, v68, v69
	v_cvt_pk_bf16_f32 v157, v70, v71
	v_cvt_pk_bf16_f32 v158, v64, v65
	v_cvt_pk_bf16_f32 v159, v66, v67
	global_store_dwordx4 v[160:161], v[156:159], off offset:256 sc1
	s_mov_b32 s1, 0x48000
	v_lshl_add_u64 v[160:161], v[148:149], 0, s[18:19]
	v_cvt_pk_bf16_f32 v156, v60, v61
	v_cvt_pk_bf16_f32 v157, v62, v63
	v_cvt_pk_bf16_f32 v158, v56, v57
	v_cvt_pk_bf16_f32 v159, v58, v59
	global_store_dwordx4 v[162:163], v[156:159], off sc1
	v_add_co_u32_e32 v162, vcc, s1, v148
	s_nop 0
	v_cvt_pk_bf16_f32 v156, v44, v45
	v_cvt_pk_bf16_f32 v157, v46, v47
	v_cvt_pk_bf16_f32 v158, v40, v41
	v_cvt_pk_bf16_f32 v159, v42, v43
	global_store_dwordx4 v[160:161], v[156:159], off offset:256 sc1
	s_mov_b64 s[18:19], 0x48000
	v_addc_co_u32_e32 v163, vcc, 0, v149, vcc
	v_cvt_pk_bf16_f32 v156, v52, v53
	v_cvt_pk_bf16_f32 v157, v54, v55
	v_cvt_pk_bf16_f32 v158, v48, v49
	v_cvt_pk_bf16_f32 v159, v50, v51
	s_mov_b32 s1, 0x50000
	v_lshl_add_u64 v[160:161], v[148:149], 0, s[18:19]
	global_store_dwordx4 v[162:163], v[156:159], off sc1
	s_mov_b64 s[18:19], 0x50000
	v_add_co_u32_e32 v162, vcc, s1, v148
	v_cvt_pk_bf16_f32 v156, v28, v29
	v_cvt_pk_bf16_f32 v157, v30, v31
	v_cvt_pk_bf16_f32 v158, v24, v25
	v_cvt_pk_bf16_f32 v159, v26, v27
	global_store_dwordx4 v[160:161], v[156:159], off offset:256 sc1
	v_lshl_add_u64 v[160:161], v[148:149], 0, s[18:19]
	v_addc_co_u32_e32 v163, vcc, 0, v149, vcc
	v_cvt_pk_bf16_f32 v156, v36, v37
	v_cvt_pk_bf16_f32 v157, v38, v39
	v_cvt_pk_bf16_f32 v158, v32, v33
	v_cvt_pk_bf16_f32 v159, v34, v35
	s_mov_b64 s[18:19], 0x58000
	s_mov_b32 s1, 0x58000
	global_store_dwordx4 v[162:163], v[156:159], off sc1
	s_nop 1
	v_cvt_pk_bf16_f32 v156, v12, v13
	v_cvt_pk_bf16_f32 v157, v14, v15
	v_cvt_pk_bf16_f32 v158, v8, v9
	v_cvt_pk_bf16_f32 v159, v10, v11
	global_store_dwordx4 v[160:161], v[156:159], off offset:256 sc1
	v_lshl_add_u64 v[160:161], v[148:149], 0, s[18:19]
	v_add_co_u32_e32 v148, vcc, s1, v148
	v_cvt_pk_bf16_f32 v156, v20, v21
	v_cvt_pk_bf16_f32 v157, v22, v23
	v_cvt_pk_bf16_f32 v158, v16, v17
	v_cvt_pk_bf16_f32 v159, v18, v19
	s_nop 1
	v_addc_co_u32_e32 v149, vcc, 0, v149, vcc
	global_store_dwordx4 v[148:149], v[156:159], off sc1
	s_nop 1
	v_cvt_pk_bf16_f32 v156, v4, v5
	v_cvt_pk_bf16_f32 v157, v6, v7
	v_cvt_pk_bf16_f32 v158, v0, v1
	v_cvt_pk_bf16_f32 v159, v2, v3
	global_store_dwordx4 v[160:161], v[156:159], off offset:256 sc1
	s_cbranch_execnz .LBB0_661
.LBB0_663:
	s_ashr_i32 s1, s0, 31
	s_lshl_b64 s[0:1], s[0:1], 21
	s_add_u32 s0, s90, s0
	s_addc_u32 s1, s91, s1
	v_lshl_add_u64 v[146:147], v[146:147], 2, s[0:1]
	v_lshlrev_b64 v[144:145], 12, v[144:145]
	s_brev_b32 s0, 63
	v_lshl_add_u64 v[144:145], v[146:147], 0, v[144:145]
	s_mov_b32 s1, -1
	v_lshl_add_u64 v[146:147], v[144:145], 0, s[0:1]
	s_brev_b32 s0, 63
	v_add_co_u32_e32 v148, vcc, s0, v144
	s_mov_b32 s0, 0xfc010000
	s_nop 0
	v_addc_co_u32_e32 v149, vcc, -1, v145, vcc
	s_mov_b32 s1, -1
	global_store_dwordx4 v[148:149], v[124:127], off sc1
	global_store_dwordx4 v[146:147], v[120:123], off offset:16 sc1
	global_store_dwordx4 v[146:147], v[108:111], off offset:512 sc1
	global_store_dwordx4 v[146:147], v[104:107], off offset:528 sc1
	s_nop 1
	v_lshl_add_u64 v[104:105], v[144:145], 0, s[0:1]
	s_mov_b32 s0, 0xfc010000
	v_add_co_u32_e32 v106, vcc, s0, v144
	s_mov_b32 s0, 0xfc020000
	s_nop 0
	v_addc_co_u32_e32 v107, vcc, -1, v145, vcc
	s_mov_b32 s1, -1
	global_store_dwordx4 v[106:107], v[116:119], off sc1
	global_store_dwordx4 v[104:105], v[112:115], off offset:16 sc1
	global_store_dwordx4 v[104:105], v[92:95], off offset:512 sc1
	global_store_dwordx4 v[104:105], v[88:91], off offset:528 sc1
	s_nop 1
	v_lshl_add_u64 v[88:89], v[144:145], 0, s[0:1]
	s_mov_b32 s0, 0xfc020000
	v_add_co_u32_e32 v90, vcc, s0, v144
	s_mov_b32 s0, 0xfc030000
	s_nop 0
	v_addc_co_u32_e32 v91, vcc, -1, v145, vcc
	s_mov_b32 s1, -1
	global_store_dwordx4 v[90:91], v[100:103], off sc1
	global_store_dwordx4 v[88:89], v[96:99], off offset:16 sc1
	global_store_dwordx4 v[88:89], v[76:79], off offset:512 sc1
	global_store_dwordx4 v[88:89], v[72:75], off offset:528 sc1
	s_nop 1
	v_lshl_add_u64 v[72:73], v[144:145], 0, s[0:1]
	s_mov_b32 s0, 0xfc030000
	v_add_co_u32_e32 v74, vcc, s0, v144
	s_mov_b32 s0, 0xfc080000
	s_nop 0
	v_addc_co_u32_e32 v75, vcc, -1, v145, vcc
	s_mov_b32 s1, -1
	global_store_dwordx4 v[74:75], v[84:87], off sc1
	global_store_dwordx4 v[72:73], v[80:83], off offset:16 sc1
	global_store_dwordx4 v[72:73], v[68:71], off offset:512 sc1
	global_store_dwordx4 v[72:73], v[64:67], off offset:528 sc1
	s_nop 1
	v_lshl_add_u64 v[64:65], v[144:145], 0, s[0:1]
	s_mov_b32 s0, 0xfc080000
	v_add_co_u32_e32 v66, vcc, s0, v144
	s_mov_b32 s0, 0xfc090000
	s_nop 0
	v_addc_co_u32_e32 v67, vcc, -1, v145, vcc
	s_mov_b32 s1, -1
	global_store_dwordx4 v[66:67], v[60:63], off sc1
	global_store_dwordx4 v[64:65], v[56:59], off offset:16 sc1
	global_store_dwordx4 v[64:65], v[44:47], off offset:512 sc1
	global_store_dwordx4 v[64:65], v[40:43], off offset:528 sc1
	s_nop 1
	v_lshl_add_u64 v[40:41], v[144:145], 0, s[0:1]
	s_mov_b32 s0, 0xfc090000
	v_add_co_u32_e32 v42, vcc, s0, v144
	s_mov_b32 s0, 0xfc0a0000
	s_nop 0
	v_addc_co_u32_e32 v43, vcc, -1, v145, vcc
	global_store_dwordx4 v[42:43], v[52:55], off sc1
	global_store_dwordx4 v[40:41], v[48:51], off offset:16 sc1
	global_store_dwordx4 v[40:41], v[28:31], off offset:512 sc1
	global_store_dwordx4 v[40:41], v[24:27], off offset:528 sc1
	s_mov_b32 s1, -1
	s_nop 0
	v_add_co_u32_e32 v26, vcc, 0xfc0a0000, v144
	v_lshl_add_u64 v[24:25], v[144:145], 0, s[0:1]
	s_nop 0
	v_addc_co_u32_e32 v27, vcc, -1, v145, vcc
	global_store_dwordx4 v[26:27], v[36:39], off sc1
	global_store_dwordx4 v[24:25], v[32:35], off offset:16 sc1
	global_store_dwordx4 v[24:25], v[12:15], off offset:512 sc1
	global_store_dwordx4 v[24:25], v[8:11], off offset:528 sc1
	s_mov_b32 s0, 0xfc0b0000
	s_mov_b32 s1, -1
	v_add_co_u32_e32 v10, vcc, 0xfc0b0000, v144
	v_lshl_add_u64 v[8:9], v[144:145], 0, s[0:1]
	s_nop 0
	v_addc_co_u32_e32 v11, vcc, -1, v145, vcc
	global_store_dwordx4 v[10:11], v[20:23], off sc1
	global_store_dwordx4 v[8:9], v[16:19], off offset:16 sc1
	global_store_dwordx4 v[8:9], v[4:7], off offset:512 sc1
	global_store_dwordx4 v[8:9], v[0:3], off offset:528 sc1
	s_and_b64 vcc, exec, s[4:5]
	s_mov_b64 s[0:1], -1
	s_cbranch_vccnz .LBB0_645

.LBB0_1095:
	v_lshlrev_b64 v[148:149], 11, v[144:145]
	v_lshl_add_u64 v[148:149], s[54:55], 0, v[148:149]
	v_lshlrev_b64 v[160:161], 1, v[146:147]
	v_lshl_add_u64 v[148:149], v[148:149], 0, v[160:161]
	v_cvt_pk_bf16_f32 v156, v124, v125
	v_cvt_pk_bf16_f32 v157, v126, v127
	v_cvt_pk_bf16_f32 v158, v120, v121
	v_cvt_pk_bf16_f32 v159, v122, v123
	global_store_dwordx4 v[148:149], v[156:159], off sc1
	s_mov_b32 s1, 0x40000
	s_mov_b64 s[20:21], 0x40000
	v_cvt_pk_bf16_f32 v156, v108, v109
	v_cvt_pk_bf16_f32 v157, v110, v111
	v_cvt_pk_bf16_f32 v158, v104, v105
	v_cvt_pk_bf16_f32 v159, v106, v107
	global_store_dwordx4 v[148:149], v[156:159], off offset:256 sc1
	s_nop 1
	v_or_b32_e32 v156, 16, v144
	v_ashrrev_i32_e32 v157, 31, v156
	v_lshlrev_b64 v[156:157], 11, v[156:157]
	v_lshl_add_u64 v[156:157], s[54:55], 0, v[156:157]
	v_lshl_add_u64 v[162:163], v[156:157], 0, v[160:161]
	v_cvt_pk_bf16_f32 v156, v116, v117
	v_cvt_pk_bf16_f32 v157, v118, v119
	v_cvt_pk_bf16_f32 v158, v112, v113
	v_cvt_pk_bf16_f32 v159, v114, v115
	global_store_dwordx4 v[162:163], v[156:159], off sc1
	s_nop 1
	v_cvt_pk_bf16_f32 v156, v92, v93
	v_cvt_pk_bf16_f32 v157, v94, v95
	v_cvt_pk_bf16_f32 v158, v88, v89
	v_cvt_pk_bf16_f32 v159, v90, v91
	global_store_dwordx4 v[162:163], v[156:159], off offset:256 sc1
	s_nop 1
	v_or_b32_e32 v156, 32, v144
	v_ashrrev_i32_e32 v157, 31, v156
	v_lshlrev_b64 v[156:157], 11, v[156:157]
	v_lshl_add_u64 v[156:157], s[54:55], 0, v[156:157]
	v_lshl_add_u64 v[162:163], v[156:157], 0, v[160:161]
	v_cvt_pk_bf16_f32 v156, v100, v101
	v_cvt_pk_bf16_f32 v157, v102, v103
	v_cvt_pk_bf16_f32 v158, v96, v97
	v_cvt_pk_bf16_f32 v159, v98, v99
	global_store_dwordx4 v[162:163], v[156:159], off sc1
	s_nop 1
	v_cvt_pk_bf16_f32 v156, v76, v77
	v_cvt_pk_bf16_f32 v157, v78, v79
	v_cvt_pk_bf16_f32 v158, v72, v73
	v_cvt_pk_bf16_f32 v159, v74, v75
	global_store_dwordx4 v[162:163], v[156:159], off offset:256 sc1
	v_add_co_u32_e32 v162, vcc, s1, v148
	s_nop 0
	v_or_b32_e32 v156, 48, v144
	v_ashrrev_i32_e32 v157, 31, v156
	v_lshlrev_b64 v[156:157], 11, v[156:157]
	v_lshl_add_u64 v[156:157], s[54:55], 0, v[156:157]
	v_lshl_add_u64 v[160:161], v[156:157], 0, v[160:161]
	v_cvt_pk_bf16_f32 v156, v84, v85
	v_cvt_pk_bf16_f32 v157, v86, v87
	v_cvt_pk_bf16_f32 v158, v80, v81
	v_cvt_pk_bf16_f32 v159, v82, v83
	global_store_dwordx4 v[160:161], v[156:159], off sc1
	v_addc_co_u32_e32 v163, vcc, 0, v149, vcc
	s_nop 0
	v_cvt_pk_bf16_f32 v156, v68, v69
	v_cvt_pk_bf16_f32 v157, v70, v71
	v_cvt_pk_bf16_f32 v158, v64, v65
	v_cvt_pk_bf16_f32 v159, v66, v67
	global_store_dwordx4 v[160:161], v[156:159], off offset:256 sc1
	s_mov_b32 s1, 0x48000
	v_lshl_add_u64 v[160:161], v[148:149], 0, s[20:21]
	v_cvt_pk_bf16_f32 v156, v60, v61
	v_cvt_pk_bf16_f32 v157, v62, v63
	v_cvt_pk_bf16_f32 v158, v56, v57
	v_cvt_pk_bf16_f32 v159, v58, v59
	global_store_dwordx4 v[162:163], v[156:159], off sc1
	v_add_co_u32_e32 v162, vcc, s1, v148
	s_nop 0
	v_cvt_pk_bf16_f32 v156, v44, v45
	v_cvt_pk_bf16_f32 v157, v46, v47
	v_cvt_pk_bf16_f32 v158, v40, v41
	v_cvt_pk_bf16_f32 v159, v42, v43
	global_store_dwordx4 v[160:161], v[156:159], off offset:256 sc1
	s_mov_b64 s[20:21], 0x48000
	v_addc_co_u32_e32 v163, vcc, 0, v149, vcc
	v_cvt_pk_bf16_f32 v156, v52, v53
	v_cvt_pk_bf16_f32 v157, v54, v55
	v_cvt_pk_bf16_f32 v158, v48, v49
	v_cvt_pk_bf16_f32 v159, v50, v51
	s_mov_b32 s1, 0x50000
	v_lshl_add_u64 v[160:161], v[148:149], 0, s[20:21]
	global_store_dwordx4 v[162:163], v[156:159], off sc1
	s_mov_b64 s[20:21], 0x50000
	v_add_co_u32_e32 v162, vcc, s1, v148
	v_cvt_pk_bf16_f32 v156, v28, v29
	v_cvt_pk_bf16_f32 v157, v30, v31
	v_cvt_pk_bf16_f32 v158, v24, v25
	v_cvt_pk_bf16_f32 v159, v26, v27
	global_store_dwordx4 v[160:161], v[156:159], off offset:256 sc1
	v_lshl_add_u64 v[160:161], v[148:149], 0, s[20:21]
	v_addc_co_u32_e32 v163, vcc, 0, v149, vcc
	v_cvt_pk_bf16_f32 v156, v36, v37
	v_cvt_pk_bf16_f32 v157, v38, v39
	v_cvt_pk_bf16_f32 v158, v32, v33
	v_cvt_pk_bf16_f32 v159, v34, v35
	s_mov_b64 s[20:21], 0x58000
	s_mov_b32 s1, 0x58000
	global_store_dwordx4 v[162:163], v[156:159], off sc1
	s_nop 1
	v_cvt_pk_bf16_f32 v156, v12, v13
	v_cvt_pk_bf16_f32 v157, v14, v15
	v_cvt_pk_bf16_f32 v158, v8, v9
	v_cvt_pk_bf16_f32 v159, v10, v11
	global_store_dwordx4 v[160:161], v[156:159], off offset:256 sc1
	v_lshl_add_u64 v[160:161], v[148:149], 0, s[20:21]
	v_add_co_u32_e32 v148, vcc, s1, v148
	v_cvt_pk_bf16_f32 v156, v20, v21
	v_cvt_pk_bf16_f32 v157, v22, v23
	v_cvt_pk_bf16_f32 v158, v16, v17
	v_cvt_pk_bf16_f32 v159, v18, v19
	s_nop 1
	v_addc_co_u32_e32 v149, vcc, 0, v149, vcc
	global_store_dwordx4 v[148:149], v[156:159], off sc1
	s_nop 1
	v_cvt_pk_bf16_f32 v156, v4, v5
	v_cvt_pk_bf16_f32 v157, v6, v7
	v_cvt_pk_bf16_f32 v158, v0, v1
	v_cvt_pk_bf16_f32 v159, v2, v3
	global_store_dwordx4 v[160:161], v[156:159], off offset:256 sc1
	s_cbranch_execnz .LBB0_1094
.LBB0_1096:
	s_ashr_i32 s1, s0, 31
	s_lshl_b64 s[0:1], s[0:1], 21
	s_add_u32 s0, s90, s0
	s_addc_u32 s1, s91, s1
	v_lshl_add_u64 v[146:147], v[146:147], 2, s[0:1]
	v_lshlrev_b64 v[144:145], 12, v[144:145]
	s_brev_b32 s0, 63
	v_lshl_add_u64 v[144:145], v[146:147], 0, v[144:145]
	s_mov_b32 s1, -1
	v_lshl_add_u64 v[146:147], v[144:145], 0, s[0:1]
	s_brev_b32 s0, 63
	v_add_co_u32_e32 v148, vcc, s0, v144
	s_mov_b32 s0, 0xfc010000
	s_nop 0
	v_addc_co_u32_e32 v149, vcc, -1, v145, vcc
	s_mov_b32 s1, -1
	global_store_dwordx4 v[148:149], v[124:127], off sc1
	global_store_dwordx4 v[146:147], v[120:123], off offset:16 sc1
	global_store_dwordx4 v[146:147], v[108:111], off offset:512 sc1
	global_store_dwordx4 v[146:147], v[104:107], off offset:528 sc1
	s_nop 1
	v_lshl_add_u64 v[104:105], v[144:145], 0, s[0:1]
	s_mov_b32 s0, 0xfc010000
	v_add_co_u32_e32 v106, vcc, s0, v144
	s_mov_b32 s0, 0xfc020000
	s_nop 0
	v_addc_co_u32_e32 v107, vcc, -1, v145, vcc
	s_mov_b32 s1, -1
	global_store_dwordx4 v[106:107], v[116:119], off sc1
	global_store_dwordx4 v[104:105], v[112:115], off offset:16 sc1
	global_store_dwordx4 v[104:105], v[92:95], off offset:512 sc1
	global_store_dwordx4 v[104:105], v[88:91], off offset:528 sc1
	s_nop 1
	v_lshl_add_u64 v[88:89], v[144:145], 0, s[0:1]
	s_mov_b32 s0, 0xfc020000
	v_add_co_u32_e32 v90, vcc, s0, v144
	s_mov_b32 s0, 0xfc030000
	s_nop 0
	v_addc_co_u32_e32 v91, vcc, -1, v145, vcc
	s_mov_b32 s1, -1
	global_store_dwordx4 v[90:91], v[100:103], off sc1
	global_store_dwordx4 v[88:89], v[96:99], off offset:16 sc1
	global_store_dwordx4 v[88:89], v[76:79], off offset:512 sc1
	global_store_dwordx4 v[88:89], v[72:75], off offset:528 sc1
	s_nop 1
	v_lshl_add_u64 v[72:73], v[144:145], 0, s[0:1]
	s_mov_b32 s0, 0xfc030000
	v_add_co_u32_e32 v74, vcc, s0, v144
	s_mov_b32 s0, 0xfc080000
	s_nop 0
	v_addc_co_u32_e32 v75, vcc, -1, v145, vcc
	s_mov_b32 s1, -1
	global_store_dwordx4 v[74:75], v[84:87], off sc1
	global_store_dwordx4 v[72:73], v[80:83], off offset:16 sc1
	global_store_dwordx4 v[72:73], v[68:71], off offset:512 sc1
	global_store_dwordx4 v[72:73], v[64:67], off offset:528 sc1
	s_nop 1
	v_lshl_add_u64 v[64:65], v[144:145], 0, s[0:1]
	s_mov_b32 s0, 0xfc080000
	v_add_co_u32_e32 v66, vcc, s0, v144
	s_mov_b32 s0, 0xfc090000
	s_nop 0
	v_addc_co_u32_e32 v67, vcc, -1, v145, vcc
	s_mov_b32 s1, -1
	global_store_dwordx4 v[66:67], v[60:63], off sc1
	global_store_dwordx4 v[64:65], v[56:59], off offset:16 sc1
	global_store_dwordx4 v[64:65], v[44:47], off offset:512 sc1
	global_store_dwordx4 v[64:65], v[40:43], off offset:528 sc1
	s_nop 1
	v_lshl_add_u64 v[40:41], v[144:145], 0, s[0:1]
	s_mov_b32 s0, 0xfc090000
	v_add_co_u32_e32 v42, vcc, s0, v144
	s_mov_b32 s0, 0xfc0a0000
	s_nop 0
	v_addc_co_u32_e32 v43, vcc, -1, v145, vcc
	global_store_dwordx4 v[42:43], v[52:55], off sc1
	global_store_dwordx4 v[40:41], v[48:51], off offset:16 sc1
	global_store_dwordx4 v[40:41], v[28:31], off offset:512 sc1
	global_store_dwordx4 v[40:41], v[24:27], off offset:528 sc1
	s_mov_b32 s1, -1
	s_nop 0
	v_add_co_u32_e32 v26, vcc, 0xfc0a0000, v144
	v_lshl_add_u64 v[24:25], v[144:145], 0, s[0:1]
	s_nop 0
	v_addc_co_u32_e32 v27, vcc, -1, v145, vcc
	global_store_dwordx4 v[26:27], v[36:39], off sc1
	global_store_dwordx4 v[24:25], v[32:35], off offset:16 sc1
	global_store_dwordx4 v[24:25], v[12:15], off offset:512 sc1
	global_store_dwordx4 v[24:25], v[8:11], off offset:528 sc1
	s_mov_b32 s0, 0xfc0b0000
	s_mov_b32 s1, -1
	v_add_co_u32_e32 v10, vcc, 0xfc0b0000, v144
	v_lshl_add_u64 v[8:9], v[144:145], 0, s[0:1]
	s_nop 0
	v_addc_co_u32_e32 v11, vcc, -1, v145, vcc
	global_store_dwordx4 v[10:11], v[20:23], off sc1
	global_store_dwordx4 v[8:9], v[16:19], off offset:16 sc1
	global_store_dwordx4 v[8:9], v[4:7], off offset:512 sc1
	global_store_dwordx4 v[8:9], v[0:3], off offset:528 sc1
	s_and_b64 vcc, exec, s[12:13]
	s_mov_b64 s[0:1], -1
	s_cbranch_vccnz .LBB0_1078

.LBB0_1372:
	s_ashr_i32 s1, s0, 31
	s_lshl_b64 s[0:1], s[0:1], 21
	s_add_u32 s0, s90, s0
	s_addc_u32 s1, s91, s1
	v_lshl_add_u64 v[146:147], v[146:147], 2, s[0:1]
	v_lshlrev_b64 v[144:145], 12, v[144:145]
	s_brev_b32 s0, 63
	v_lshl_add_u64 v[144:145], v[146:147], 0, v[144:145]
	s_mov_b32 s1, -1
	v_lshl_add_u64 v[146:147], v[144:145], 0, s[0:1]
	s_brev_b32 s0, 63
	v_add_co_u32_e32 v148, vcc, s0, v144
	s_mov_b32 s0, 0xfc010000
	s_nop 0
	v_addc_co_u32_e32 v149, vcc, -1, v145, vcc
	s_mov_b32 s1, -1
	global_store_dwordx4 v[148:149], v[124:127], off sc1
	global_store_dwordx4 v[146:147], v[120:123], off offset:16 sc1
	global_store_dwordx4 v[146:147], v[108:111], off offset:512 sc1
	global_store_dwordx4 v[146:147], v[104:107], off offset:528 sc1
	s_nop 1
	v_lshl_add_u64 v[104:105], v[144:145], 0, s[0:1]
	s_mov_b32 s0, 0xfc010000
	v_add_co_u32_e32 v106, vcc, s0, v144
	s_mov_b32 s0, 0xfc020000
	s_nop 0
	v_addc_co_u32_e32 v107, vcc, -1, v145, vcc
	s_mov_b32 s1, -1
	global_store_dwordx4 v[106:107], v[116:119], off sc1
	global_store_dwordx4 v[104:105], v[112:115], off offset:16 sc1
	global_store_dwordx4 v[104:105], v[92:95], off offset:512 sc1
	global_store_dwordx4 v[104:105], v[88:91], off offset:528 sc1
	s_nop 1
	v_lshl_add_u64 v[88:89], v[144:145], 0, s[0:1]
	s_mov_b32 s0, 0xfc020000
	v_add_co_u32_e32 v90, vcc, s0, v144
	s_mov_b32 s0, 0xfc030000
	s_nop 0
	v_addc_co_u32_e32 v91, vcc, -1, v145, vcc
	s_mov_b32 s1, -1
	global_store_dwordx4 v[90:91], v[100:103], off sc1
	global_store_dwordx4 v[88:89], v[96:99], off offset:16 sc1
	global_store_dwordx4 v[88:89], v[76:79], off offset:512 sc1
	global_store_dwordx4 v[88:89], v[72:75], off offset:528 sc1
	s_nop 1
	v_lshl_add_u64 v[72:73], v[144:145], 0, s[0:1]
	s_mov_b32 s0, 0xfc030000
	v_add_co_u32_e32 v74, vcc, s0, v144
	s_mov_b32 s0, 0xfc080000
	s_nop 0
	v_addc_co_u32_e32 v75, vcc, -1, v145, vcc
	s_mov_b32 s1, -1
	global_store_dwordx4 v[74:75], v[84:87], off sc1
	global_store_dwordx4 v[72:73], v[80:83], off offset:16 sc1
	global_store_dwordx4 v[72:73], v[68:71], off offset:512 sc1
	global_store_dwordx4 v[72:73], v[64:67], off offset:528 sc1
	s_nop 1
	v_lshl_add_u64 v[64:65], v[144:145], 0, s[0:1]
	s_mov_b32 s0, 0xfc080000
	v_add_co_u32_e32 v66, vcc, s0, v144
	s_mov_b32 s0, 0xfc090000
	s_nop 0
	v_addc_co_u32_e32 v67, vcc, -1, v145, vcc
	s_mov_b32 s1, -1
	global_store_dwordx4 v[66:67], v[60:63], off sc1
	global_store_dwordx4 v[64:65], v[56:59], off offset:16 sc1
	global_store_dwordx4 v[64:65], v[44:47], off offset:512 sc1
	global_store_dwordx4 v[64:65], v[40:43], off offset:528 sc1
	s_nop 1
	v_lshl_add_u64 v[40:41], v[144:145], 0, s[0:1]
	s_mov_b32 s0, 0xfc090000
	v_add_co_u32_e32 v42, vcc, s0, v144
	s_mov_b32 s0, 0xfc0a0000
	s_nop 0
	v_addc_co_u32_e32 v43, vcc, -1, v145, vcc
	global_store_dwordx4 v[42:43], v[52:55], off sc1
	global_store_dwordx4 v[40:41], v[48:51], off offset:16 sc1
	global_store_dwordx4 v[40:41], v[28:31], off offset:512 sc1
	global_store_dwordx4 v[40:41], v[24:27], off offset:528 sc1
	s_mov_b32 s1, -1
	s_nop 0
	v_add_co_u32_e32 v26, vcc, 0xfc0a0000, v144
	v_lshl_add_u64 v[24:25], v[144:145], 0, s[0:1]
	s_nop 0
	v_addc_co_u32_e32 v27, vcc, -1, v145, vcc
	global_store_dwordx4 v[26:27], v[36:39], off sc1
	global_store_dwordx4 v[24:25], v[32:35], off offset:16 sc1
	global_store_dwordx4 v[24:25], v[12:15], off offset:512 sc1
	global_store_dwordx4 v[24:25], v[8:11], off offset:528 sc1
	s_mov_b32 s0, 0xfc0b0000
	s_mov_b32 s1, -1
	v_add_co_u32_e32 v10, vcc, 0xfc0b0000, v144
	v_lshl_add_u64 v[8:9], v[144:145], 0, s[0:1]
	s_nop 0
	v_addc_co_u32_e32 v11, vcc, -1, v145, vcc
	global_store_dwordx4 v[10:11], v[20:23], off sc1
	global_store_dwordx4 v[8:9], v[16:19], off offset:16 sc1
	global_store_dwordx4 v[8:9], v[4:7], off offset:512 sc1
	global_store_dwordx4 v[8:9], v[0:3], off offset:528 sc1
	s_and_b64 vcc, exec, s[16:17]
	s_mov_b64 s[0:1], -1
	s_cbranch_vccnz .LBB0_1354

.LBB0_2514:
	v_lshlrev_b64 v[148:149], 11, v[144:145]
	v_lshl_add_u64 v[148:149], s[54:55], 0, v[148:149]
	v_lshlrev_b64 v[160:161], 1, v[146:147]
	v_lshl_add_u64 v[148:149], v[148:149], 0, v[160:161]
	v_cvt_pk_bf16_f32 v156, v124, v125
	v_cvt_pk_bf16_f32 v157, v126, v127
	v_cvt_pk_bf16_f32 v158, v120, v121
	v_cvt_pk_bf16_f32 v159, v122, v123
	global_store_dwordx4 v[148:149], v[156:159], off sc1
	s_mov_b32 s1, 0x40000
	s_mov_b64 s[22:23], 0x40000
	v_cvt_pk_bf16_f32 v156, v108, v109
	v_cvt_pk_bf16_f32 v157, v110, v111
	v_cvt_pk_bf16_f32 v158, v104, v105
	v_cvt_pk_bf16_f32 v159, v106, v107
	global_store_dwordx4 v[148:149], v[156:159], off offset:256 sc1
	s_nop 1
	v_or_b32_e32 v156, 16, v144
	v_ashrrev_i32_e32 v157, 31, v156
	v_lshlrev_b64 v[156:157], 11, v[156:157]
	v_lshl_add_u64 v[156:157], s[54:55], 0, v[156:157]
	v_lshl_add_u64 v[162:163], v[156:157], 0, v[160:161]
	v_cvt_pk_bf16_f32 v156, v116, v117
	v_cvt_pk_bf16_f32 v157, v118, v119
	v_cvt_pk_bf16_f32 v158, v112, v113
	v_cvt_pk_bf16_f32 v159, v114, v115
	global_store_dwordx4 v[162:163], v[156:159], off sc1
	s_nop 1
	v_cvt_pk_bf16_f32 v156, v92, v93
	v_cvt_pk_bf16_f32 v157, v94, v95
	v_cvt_pk_bf16_f32 v158, v88, v89
	v_cvt_pk_bf16_f32 v159, v90, v91
	global_store_dwordx4 v[162:163], v[156:159], off offset:256 sc1
	s_nop 1
	v_or_b32_e32 v156, 32, v144
	v_ashrrev_i32_e32 v157, 31, v156
	v_lshlrev_b64 v[156:157], 11, v[156:157]
	v_lshl_add_u64 v[156:157], s[54:55], 0, v[156:157]
	v_lshl_add_u64 v[162:163], v[156:157], 0, v[160:161]
	v_cvt_pk_bf16_f32 v156, v100, v101
	v_cvt_pk_bf16_f32 v157, v102, v103
	v_cvt_pk_bf16_f32 v158, v96, v97
	v_cvt_pk_bf16_f32 v159, v98, v99
	global_store_dwordx4 v[162:163], v[156:159], off sc1
	s_nop 1
	v_cvt_pk_bf16_f32 v156, v76, v77
	v_cvt_pk_bf16_f32 v157, v78, v79
	v_cvt_pk_bf16_f32 v158, v72, v73
	v_cvt_pk_bf16_f32 v159, v74, v75
	global_store_dwordx4 v[162:163], v[156:159], off offset:256 sc1
	v_add_co_u32_e32 v162, vcc, s1, v148
	s_nop 0
	v_or_b32_e32 v156, 48, v144
	v_ashrrev_i32_e32 v157, 31, v156
	v_lshlrev_b64 v[156:157], 11, v[156:157]
	v_lshl_add_u64 v[156:157], s[54:55], 0, v[156:157]
	v_lshl_add_u64 v[160:161], v[156:157], 0, v[160:161]
	v_cvt_pk_bf16_f32 v156, v84, v85
	v_cvt_pk_bf16_f32 v157, v86, v87
	v_cvt_pk_bf16_f32 v158, v80, v81
	v_cvt_pk_bf16_f32 v159, v82, v83
	global_store_dwordx4 v[160:161], v[156:159], off sc1
	v_addc_co_u32_e32 v163, vcc, 0, v149, vcc
	s_nop 0
	v_cvt_pk_bf16_f32 v156, v68, v69
	v_cvt_pk_bf16_f32 v157, v70, v71
	v_cvt_pk_bf16_f32 v158, v64, v65
	v_cvt_pk_bf16_f32 v159, v66, v67
	global_store_dwordx4 v[160:161], v[156:159], off offset:256 sc1
	s_mov_b32 s1, 0x48000
	v_lshl_add_u64 v[160:161], v[148:149], 0, s[22:23]
	v_cvt_pk_bf16_f32 v156, v60, v61
	v_cvt_pk_bf16_f32 v157, v62, v63
	v_cvt_pk_bf16_f32 v158, v56, v57
	v_cvt_pk_bf16_f32 v159, v58, v59
	global_store_dwordx4 v[162:163], v[156:159], off sc1
	v_add_co_u32_e32 v162, vcc, s1, v148
	s_nop 0
	v_cvt_pk_bf16_f32 v156, v44, v45
	v_cvt_pk_bf16_f32 v157, v46, v47
	v_cvt_pk_bf16_f32 v158, v40, v41
	v_cvt_pk_bf16_f32 v159, v42, v43
	global_store_dwordx4 v[160:161], v[156:159], off offset:256 sc1
	s_mov_b64 s[22:23], 0x48000
	v_addc_co_u32_e32 v163, vcc, 0, v149, vcc
	v_cvt_pk_bf16_f32 v156, v52, v53
	v_cvt_pk_bf16_f32 v157, v54, v55
	v_cvt_pk_bf16_f32 v158, v48, v49
	v_cvt_pk_bf16_f32 v159, v50, v51
	s_mov_b32 s1, 0x50000
	v_lshl_add_u64 v[160:161], v[148:149], 0, s[22:23]
	global_store_dwordx4 v[162:163], v[156:159], off sc1
	s_mov_b64 s[22:23], 0x50000
	v_add_co_u32_e32 v162, vcc, s1, v148
	v_cvt_pk_bf16_f32 v156, v28, v29
	v_cvt_pk_bf16_f32 v157, v30, v31
	v_cvt_pk_bf16_f32 v158, v24, v25
	v_cvt_pk_bf16_f32 v159, v26, v27
	global_store_dwordx4 v[160:161], v[156:159], off offset:256 sc1
	v_lshl_add_u64 v[160:161], v[148:149], 0, s[22:23]
	v_addc_co_u32_e32 v163, vcc, 0, v149, vcc
	v_cvt_pk_bf16_f32 v156, v36, v37
	v_cvt_pk_bf16_f32 v157, v38, v39
	v_cvt_pk_bf16_f32 v158, v32, v33
	v_cvt_pk_bf16_f32 v159, v34, v35
	s_mov_b64 s[22:23], 0x58000
	s_mov_b32 s1, 0x58000
	global_store_dwordx4 v[162:163], v[156:159], off sc1
	s_nop 1
	v_cvt_pk_bf16_f32 v156, v12, v13
	v_cvt_pk_bf16_f32 v157, v14, v15
	v_cvt_pk_bf16_f32 v158, v8, v9
	v_cvt_pk_bf16_f32 v159, v10, v11
	global_store_dwordx4 v[160:161], v[156:159], off offset:256 sc1
	v_lshl_add_u64 v[160:161], v[148:149], 0, s[22:23]
	v_add_co_u32_e32 v148, vcc, s1, v148
	v_cvt_pk_bf16_f32 v156, v20, v21
	v_cvt_pk_bf16_f32 v157, v22, v23
	v_cvt_pk_bf16_f32 v158, v16, v17
	v_cvt_pk_bf16_f32 v159, v18, v19
	s_nop 1
	v_addc_co_u32_e32 v149, vcc, 0, v149, vcc
	global_store_dwordx4 v[148:149], v[156:159], off sc1
	s_nop 1
	v_cvt_pk_bf16_f32 v156, v4, v5
	v_cvt_pk_bf16_f32 v157, v6, v7
	v_cvt_pk_bf16_f32 v158, v0, v1
	v_cvt_pk_bf16_f32 v159, v2, v3
	global_store_dwordx4 v[160:161], v[156:159], off offset:256 sc1
	s_cbranch_execnz .LBB0_2513

.LBB0_2790:
	v_lshlrev_b64 v[148:149], 11, v[144:145]
	v_lshl_add_u64 v[148:149], s[54:55], 0, v[148:149]
	v_lshlrev_b64 v[160:161], 1, v[146:147]
	v_lshl_add_u64 v[148:149], v[148:149], 0, v[160:161]
	v_cvt_pk_bf16_f32 v156, v124, v125
	v_cvt_pk_bf16_f32 v157, v126, v127
	v_cvt_pk_bf16_f32 v158, v120, v121
	v_cvt_pk_bf16_f32 v159, v122, v123
	global_store_dwordx4 v[148:149], v[156:159], off sc1
	s_mov_b32 s1, 0x40000
	s_mov_b64 s[38:39], 0x40000
	v_cvt_pk_bf16_f32 v156, v108, v109
	v_cvt_pk_bf16_f32 v157, v110, v111
	v_cvt_pk_bf16_f32 v158, v100, v101
	v_cvt_pk_bf16_f32 v159, v102, v103
	global_store_dwordx4 v[148:149], v[156:159], off offset:256 sc1
	s_nop 1
	v_or_b32_e32 v156, 16, v144
	v_ashrrev_i32_e32 v157, 31, v156
	v_lshlrev_b64 v[156:157], 11, v[156:157]
	v_lshl_add_u64 v[156:157], s[54:55], 0, v[156:157]
	v_lshl_add_u64 v[162:163], v[156:157], 0, v[160:161]
	v_cvt_pk_bf16_f32 v156, v116, v117
	v_cvt_pk_bf16_f32 v157, v118, v119
	v_cvt_pk_bf16_f32 v158, v112, v113
	v_cvt_pk_bf16_f32 v159, v114, v115
	global_store_dwordx4 v[162:163], v[156:159], off sc1
	s_nop 1
	v_cvt_pk_bf16_f32 v156, v92, v93
	v_cvt_pk_bf16_f32 v157, v94, v95
	v_cvt_pk_bf16_f32 v158, v84, v85
	v_cvt_pk_bf16_f32 v159, v86, v87
	global_store_dwordx4 v[162:163], v[156:159], off offset:256 sc1
	s_nop 1
	v_or_b32_e32 v156, 32, v144
	v_ashrrev_i32_e32 v157, 31, v156
	v_lshlrev_b64 v[156:157], 11, v[156:157]
	v_lshl_add_u64 v[156:157], s[54:55], 0, v[156:157]
	v_lshl_add_u64 v[162:163], v[156:157], 0, v[160:161]
	v_cvt_pk_bf16_f32 v156, v104, v105
	v_cvt_pk_bf16_f32 v157, v106, v107
	v_cvt_pk_bf16_f32 v158, v96, v97
	v_cvt_pk_bf16_f32 v159, v98, v99
	global_store_dwordx4 v[162:163], v[156:159], off sc1
	s_nop 1
	v_cvt_pk_bf16_f32 v156, v76, v77
	v_cvt_pk_bf16_f32 v157, v78, v79
	v_cvt_pk_bf16_f32 v158, v72, v73
	v_cvt_pk_bf16_f32 v159, v74, v75
	global_store_dwordx4 v[162:163], v[156:159], off offset:256 sc1
	v_add_co_u32_e32 v162, vcc, s1, v148
	s_nop 0
	v_or_b32_e32 v156, 48, v144
	v_ashrrev_i32_e32 v157, 31, v156
	v_lshlrev_b64 v[156:157], 11, v[156:157]
	v_lshl_add_u64 v[156:157], s[54:55], 0, v[156:157]
	v_lshl_add_u64 v[160:161], v[156:157], 0, v[160:161]
	v_cvt_pk_bf16_f32 v156, v88, v89
	v_cvt_pk_bf16_f32 v157, v90, v91
	v_cvt_pk_bf16_f32 v158, v80, v81
	v_cvt_pk_bf16_f32 v159, v82, v83
	global_store_dwordx4 v[160:161], v[156:159], off sc1
	v_addc_co_u32_e32 v163, vcc, 0, v149, vcc
	s_nop 0
	v_cvt_pk_bf16_f32 v156, v68, v69
	v_cvt_pk_bf16_f32 v157, v70, v71
	v_cvt_pk_bf16_f32 v158, v64, v65
	v_cvt_pk_bf16_f32 v159, v66, v67
	global_store_dwordx4 v[160:161], v[156:159], off offset:256 sc1
	s_mov_b32 s1, 0x48000
	v_lshl_add_u64 v[160:161], v[148:149], 0, s[38:39]
	v_cvt_pk_bf16_f32 v156, v60, v61
	v_cvt_pk_bf16_f32 v157, v62, v63
	v_cvt_pk_bf16_f32 v158, v56, v57
	v_cvt_pk_bf16_f32 v159, v58, v59
	global_store_dwordx4 v[162:163], v[156:159], off sc1
	v_add_co_u32_e32 v162, vcc, s1, v148
	s_nop 0
	v_cvt_pk_bf16_f32 v156, v44, v45
	v_cvt_pk_bf16_f32 v157, v46, v47
	v_cvt_pk_bf16_f32 v158, v36, v37
	v_cvt_pk_bf16_f32 v159, v38, v39
	global_store_dwordx4 v[160:161], v[156:159], off offset:256 sc1
	s_mov_b64 s[38:39], 0x48000
	v_addc_co_u32_e32 v163, vcc, 0, v149, vcc
	v_cvt_pk_bf16_f32 v156, v52, v53
	v_cvt_pk_bf16_f32 v157, v54, v55
	v_cvt_pk_bf16_f32 v158, v48, v49
	v_cvt_pk_bf16_f32 v159, v50, v51
	v_lshl_add_u64 v[160:161], v[148:149], 0, s[38:39]
	global_store_dwordx4 v[162:163], v[156:159], off sc1
	s_mov_b64 s[38:39], 0x50000
	v_add_co_u32_e32 v162, vcc, s59, v148
	v_cvt_pk_bf16_f32 v156, v28, v29
	v_cvt_pk_bf16_f32 v157, v30, v31
	v_cvt_pk_bf16_f32 v158, v20, v21
	v_cvt_pk_bf16_f32 v159, v22, v23
	global_store_dwordx4 v[160:161], v[156:159], off offset:256 sc1
	v_lshl_add_u64 v[160:161], v[148:149], 0, s[38:39]
	v_addc_co_u32_e32 v163, vcc, 0, v149, vcc
	v_cvt_pk_bf16_f32 v156, v40, v41
	v_cvt_pk_bf16_f32 v157, v42, v43
	v_cvt_pk_bf16_f32 v158, v32, v33
	v_cvt_pk_bf16_f32 v159, v34, v35
	global_store_dwordx4 v[162:163], v[156:159], off sc1
	s_nop 1
	v_cvt_pk_bf16_f32 v156, v12, v13
	v_cvt_pk_bf16_f32 v157, v14, v15
	v_cvt_pk_bf16_f32 v158, v8, v9
	v_cvt_pk_bf16_f32 v159, v10, v11
	global_store_dwordx4 v[160:161], v[156:159], off offset:256 sc1
	v_lshl_add_u64 v[160:161], v[148:149], 0, s[14:15]
	v_add_co_u32_e32 v148, vcc, s60, v148
	v_cvt_pk_bf16_f32 v156, v24, v25
	v_cvt_pk_bf16_f32 v157, v26, v27
	v_cvt_pk_bf16_f32 v158, v16, v17
	v_cvt_pk_bf16_f32 v159, v18, v19
	s_nop 1
	v_addc_co_u32_e32 v149, vcc, 0, v149, vcc
	global_store_dwordx4 v[148:149], v[156:159], off sc1
	s_nop 1
	v_cvt_pk_bf16_f32 v156, v4, v5
	v_cvt_pk_bf16_f32 v157, v6, v7
	v_cvt_pk_bf16_f32 v158, v0, v1
	v_cvt_pk_bf16_f32 v159, v2, v3
	global_store_dwordx4 v[160:161], v[156:159], off offset:256 sc1
	s_cbranch_execnz .LBB0_2789
.LBB0_2791:
	s_ashr_i32 s1, s0, 31
	s_lshl_b64 s[0:1], s[0:1], 21
	s_add_u32 s0, s90, s0
	s_addc_u32 s1, s91, s1
	v_lshl_add_u64 v[146:147], v[146:147], 2, s[0:1]
	v_lshlrev_b64 v[144:145], 12, v[144:145]
	v_lshl_add_u64 v[144:145], v[146:147], 0, v[144:145]
	v_add_co_u32_e32 v148, vcc, s61, v144
	v_lshl_add_u64 v[146:147], v[144:145], 0, s[16:17]
	s_nop 0
	v_addc_co_u32_e32 v149, vcc, -1, v145, vcc
	global_store_dwordx4 v[148:149], v[124:127], off sc1
	global_store_dwordx4 v[146:147], v[120:123], off offset:16 sc1
	global_store_dwordx4 v[146:147], v[108:111], off offset:512 sc1
	global_store_dwordx4 v[146:147], v[100:103], off offset:528 sc1
	s_nop 1
	v_add_co_u32_e32 v102, vcc, s62, v144
	v_lshl_add_u64 v[100:101], v[144:145], 0, s[18:19]
	s_nop 0
	v_addc_co_u32_e32 v103, vcc, -1, v145, vcc
	global_store_dwordx4 v[102:103], v[116:119], off sc1
	global_store_dwordx4 v[100:101], v[112:115], off offset:16 sc1
	global_store_dwordx4 v[100:101], v[92:95], off offset:512 sc1
	global_store_dwordx4 v[100:101], v[84:87], off offset:528 sc1
	s_nop 1
	v_add_co_u32_e32 v86, vcc, s63, v144
	v_lshl_add_u64 v[84:85], v[144:145], 0, s[20:21]
	s_nop 0
	v_addc_co_u32_e32 v87, vcc, -1, v145, vcc
	global_store_dwordx4 v[86:87], v[104:107], off sc1
	global_store_dwordx4 v[84:85], v[96:99], off offset:16 sc1
	global_store_dwordx4 v[84:85], v[76:79], off offset:512 sc1
	global_store_dwordx4 v[84:85], v[72:75], off offset:528 sc1
	s_nop 1
	v_add_co_u32_e32 v74, vcc, s64, v144
	v_lshl_add_u64 v[72:73], v[144:145], 0, s[22:23]
	s_nop 0
	v_addc_co_u32_e32 v75, vcc, -1, v145, vcc
	global_store_dwordx4 v[74:75], v[88:91], off sc1
	global_store_dwordx4 v[72:73], v[80:83], off offset:16 sc1
	global_store_dwordx4 v[72:73], v[68:71], off offset:512 sc1
	global_store_dwordx4 v[72:73], v[64:67], off offset:528 sc1
	s_nop 1
	v_add_co_u32_e32 v66, vcc, s65, v144
	v_lshl_add_u64 v[64:65], v[144:145], 0, s[24:25]
	s_nop 0
	v_addc_co_u32_e32 v67, vcc, -1, v145, vcc
	global_store_dwordx4 v[66:67], v[60:63], off sc1
	global_store_dwordx4 v[64:65], v[56:59], off offset:16 sc1
	global_store_dwordx4 v[64:65], v[44:47], off offset:512 sc1
	global_store_dwordx4 v[64:65], v[36:39], off offset:528 sc1
	s_nop 1
	v_add_co_u32_e32 v38, vcc, s66, v144
	v_lshl_add_u64 v[36:37], v[144:145], 0, s[26:27]
	s_nop 0
	v_addc_co_u32_e32 v39, vcc, -1, v145, vcc
	global_store_dwordx4 v[38:39], v[52:55], off sc1
	global_store_dwordx4 v[36:37], v[48:51], off offset:16 sc1
	global_store_dwordx4 v[36:37], v[28:31], off offset:512 sc1
	global_store_dwordx4 v[36:37], v[20:23], off offset:528 sc1
	s_nop 1
	v_add_co_u32_e32 v22, vcc, 0xfc0a0000, v144
	v_lshl_add_u64 v[20:21], v[144:145], 0, s[28:29]
	s_nop 0
	v_addc_co_u32_e32 v23, vcc, -1, v145, vcc
	global_store_dwordx4 v[22:23], v[40:43], off sc1
	global_store_dwordx4 v[20:21], v[32:35], off offset:16 sc1
	global_store_dwordx4 v[20:21], v[12:15], off offset:512 sc1
	global_store_dwordx4 v[20:21], v[8:11], off offset:528 sc1
	s_nop 1
	v_add_co_u32_e32 v10, vcc, 0xfc0b0000, v144
	v_lshl_add_u64 v[8:9], v[144:145], 0, s[30:31]
	s_nop 0
	v_addc_co_u32_e32 v11, vcc, -1, v145, vcc
	global_store_dwordx4 v[10:11], v[24:27], off sc1
	global_store_dwordx4 v[8:9], v[16:19], off offset:16 sc1
	global_store_dwordx4 v[8:9], v[4:7], off offset:512 sc1
	global_store_dwordx4 v[8:9], v[0:3], off offset:528 sc1
	s_and_b64 vcc, exec, s[4:5]
	s_mov_b64 s[0:1], -1
	s_cbranch_vccnz .LBB0_2773
